# v21 plus: scoring loops compute the second score row's store address once per iteration (immediate offsets for tiles 1-3); layer-0 loop waits once per tile
# baseline (speedup 1.0000x reference)
.LBB0_797:
	ds_read_b128 v[2:5], v139
	ds_read_b128 v[18:21], v139 offset:32
	ds_read_b128 v[22:25], v139 offset:64
	ds_read_b128 v[26:29], v139 offset:96
	ds_read_b128 v[34:37], v139 offset:4608
	ds_read_b128 v[30:33], v139 offset:4640
	ds_read_b128 v[174:177], v139 offset:4672
	ds_read_b128 v[184:187], v139 offset:4704
	ds_read_b128 v[188:191], v139 offset:9216
	ds_read_b128 v[192:195], v139 offset:9248
	ds_read_b128 v[196:199], v139 offset:9280
	ds_read_b128 v[200:203], v139 offset:9312
	s_mov_b32 s8, s7
	s_add_i32 s7, s7, 4
	s_add_i32 s8, s8, 7
	s_waitcnt lgkmcnt(8)
	v_mfma_f32_32x32x16_bf16 v[2:17], v[58:61], v[2:5], 0
	s_cmp_ge_i32 s8, s6
	v_mfma_f32_32x32x16_bf16 v[2:17], v[54:57], v[18:21], v[2:17]
	v_mfma_f32_32x32x16_bf16 v[2:17], v[50:53], v[22:25], v[2:17]
	v_mfma_f32_32x32x16_bf16 v[2:17], v[62:65], v[26:29], v[2:17]
	s_waitcnt lgkmcnt(4)
	v_mfma_f32_32x32x16_bf16 v[34:49], v[58:61], v[34:37], 0
	s_nop 7
	s_nop 1
	v_max_f32_e32 v2, 0, v2
	v_fma_f32 v140, v120, v2, 0
	v_max_f32_e32 v2, 0, v10
	v_fma_f32 v141, v121, v2, 0
	v_mfma_f32_32x32x16_bf16 v[34:49], v[54:57], v[30:33], v[34:49]
	v_max_f32_e32 v2, 0, v3
	v_fmac_f32_e32 v140, v122, v2
	v_max_f32_e32 v2, 0, v11
	v_fmac_f32_e32 v141, v123, v2
	v_mfma_f32_32x32x16_bf16 v[34:49], v[50:53], v[174:177], v[34:49]
	v_max_f32_e32 v2, 0, v4
	v_fmac_f32_e32 v140, v124, v2
	v_max_f32_e32 v2, 0, v12
	v_fmac_f32_e32 v141, v125, v2
	v_mfma_f32_32x32x16_bf16 v[34:49], v[62:65], v[184:187], v[34:49]
	v_max_f32_e32 v2, 0, v5
	v_fmac_f32_e32 v140, v126, v2
	v_max_f32_e32 v2, 0, v13
	v_fmac_f32_e32 v141, v127, v2
	s_waitcnt lgkmcnt(0)
	v_mfma_f32_32x32x16_bf16 v[18:33], v[58:61], v[188:191], 0
	v_max_f32_e32 v2, 0, v6
	v_fmac_f32_e32 v140, v128, v2
	v_max_f32_e32 v2, 0, v14
	v_fmac_f32_e32 v141, v129, v2
	v_mfma_f32_32x32x16_bf16 v[18:33], v[54:57], v[192:195], v[18:33]
	v_max_f32_e32 v2, 0, v7
	v_fmac_f32_e32 v140, v130, v2
	v_max_f32_e32 v2, 0, v15
	v_fmac_f32_e32 v141, v131, v2
	v_mfma_f32_32x32x16_bf16 v[18:33], v[50:53], v[196:199], v[18:33]
	v_max_f32_e32 v2, 0, v8
	v_fmac_f32_e32 v140, v132, v2
	v_max_f32_e32 v2, 0, v16
	v_fmac_f32_e32 v141, v133, v2
	v_max_f32_e32 v2, 0, v9
	v_mfma_f32_32x32x16_bf16 v[18:33], v[62:65], v[200:203], v[18:33]
	ds_read_b128 v[110:113], v139 offset:13824
	ds_read_b128 v[106:109], v139 offset:13856
	ds_read_b128 v[102:105], v139 offset:13888
	ds_read_b128 v[98:101], v139 offset:13920
	v_fmac_f32_e32 v140, v134, v2
	v_max_f32_e32 v2, 0, v17
	v_fmac_f32_e32 v141, v135, v2
	v_max_f32_e32 v34, 0, v34
	s_waitcnt lgkmcnt(3)
	v_mfma_f32_32x32x16_bf16 v[2:17], v[58:61], v[110:113], 0
	s_nop 1
	v_max_f32_e32 v18, 0, v18
	v_add_u32_e32 v139, 0x4800, v139
	s_waitcnt lgkmcnt(2)
	v_mfma_f32_32x32x16_bf16 v[2:17], v[54:57], v[106:109], v[2:17]
	v_add_f32_e32 v106, 0, v141
	s_waitcnt lgkmcnt(1)
	v_mfma_f32_32x32x16_bf16 v[2:17], v[50:53], v[102:105], v[2:17]
	v_add_f32_e32 v102, 0, v140
	v_ashrrev_i32_e32 v103, 31, v102
	v_lshlrev_b64 v[104:105], 2, v[148:149]
	v_bitop3_b32 v107, v103, v102, s75 bitop3:0x36
	v_lshl_add_u64 v[102:103], v[116:117], 0, v[104:105]
	global_store_dword v[102:103], v107, off nt
	v_ashrrev_i32_e32 v107, 31, v106
	v_bitop3_b32 v106, v107, v106, s75 bitop3:0x36
	v_lshl_add_u64 v[208:209], v[118:119], 0, v[104:105]
	global_store_dword v[208:209], v106, off nt
	v_fma_f32 v104, v120, v34, 0
	v_max_f32_e32 v34, 0, v42
	v_fma_f32 v42, v121, v34, 0
	v_max_f32_e32 v34, 0, v35
	v_fmac_f32_e32 v104, v122, v34
	v_max_f32_e32 v34, 0, v43
	v_fmac_f32_e32 v42, v123, v34
	v_max_f32_e32 v34, 0, v36
	v_fmac_f32_e32 v104, v124, v34
	v_max_f32_e32 v34, 0, v44
	v_fmac_f32_e32 v42, v125, v34
	v_max_f32_e32 v34, 0, v37
	v_fmac_f32_e32 v104, v126, v34
	v_max_f32_e32 v34, 0, v45
	v_fmac_f32_e32 v42, v127, v34
	v_max_f32_e32 v34, 0, v38
	v_fmac_f32_e32 v104, v128, v34
	v_max_f32_e32 v34, 0, v46
	v_fmac_f32_e32 v42, v129, v34
	v_max_f32_e32 v34, 0, v39
	v_fmac_f32_e32 v104, v130, v34
	v_max_f32_e32 v34, 0, v47
	v_fmac_f32_e32 v42, v131, v34
	v_max_f32_e32 v34, 0, v40
	v_fmac_f32_e32 v104, v132, v34
	v_max_f32_e32 v34, 0, v48
	v_fmac_f32_e32 v42, v133, v34
	v_max_f32_e32 v34, 0, v41
	v_fmac_f32_e32 v104, v134, v34
	v_max_f32_e32 v34, 0, v49
	v_add_f32_e32 v35, 0, v104
	v_fmac_f32_e32 v42, v135, v34
	v_ashrrev_i32_e32 v37, 31, v35
	v_add_f32_e32 v36, 0, v42
	v_bitop3_b32 v37, v37, v35, s75 bitop3:0x36
	global_store_dword v[102:103], v37, off offset:128 nt
	v_ashrrev_i32_e32 v37, 31, v36
	v_bitop3_b32 v36, v37, v36, s75 bitop3:0x36
	global_store_dword v[208:209], v36, off offset:128 nt
	v_fma_f32 v34, v120, v18, 0
	v_max_f32_e32 v18, 0, v26
	v_fma_f32 v26, v121, v18, 0
	v_max_f32_e32 v18, 0, v19
	v_fmac_f32_e32 v34, v122, v18
	v_max_f32_e32 v18, 0, v27
	v_fmac_f32_e32 v26, v123, v18
	v_max_f32_e32 v18, 0, v20
	v_fmac_f32_e32 v34, v124, v18
	v_max_f32_e32 v18, 0, v28
	v_fmac_f32_e32 v26, v125, v18
	v_max_f32_e32 v18, 0, v21
	v_fmac_f32_e32 v34, v126, v18
	v_max_f32_e32 v18, 0, v29
	v_fmac_f32_e32 v26, v127, v18
	v_max_f32_e32 v18, 0, v22
	v_fmac_f32_e32 v34, v128, v18
	v_max_f32_e32 v18, 0, v30
	v_fmac_f32_e32 v26, v129, v18
	v_max_f32_e32 v18, 0, v23
	v_fmac_f32_e32 v34, v130, v18
	v_max_f32_e32 v18, 0, v31
	v_fmac_f32_e32 v26, v131, v18
	v_max_f32_e32 v18, 0, v24
	v_fmac_f32_e32 v34, v132, v18
	s_waitcnt lgkmcnt(0)
	v_mfma_f32_32x32x16_bf16 v[2:17], v[62:65], v[98:101], v[2:17]
	v_max_f32_e32 v18, 0, v32
	v_fmac_f32_e32 v26, v133, v18
	v_max_f32_e32 v18, 0, v25
	v_fmac_f32_e32 v34, v134, v18
	v_max_f32_e32 v18, 0, v33
	v_add_f32_e32 v19, 0, v34
	v_fmac_f32_e32 v26, v135, v18
	v_ashrrev_i32_e32 v21, 31, v19
	v_add_f32_e32 v20, 0, v26
	v_bitop3_b32 v21, v21, v19, s75 bitop3:0x36
	global_store_dword v[102:103], v21, off offset:256 nt
	v_ashrrev_i32_e32 v21, 31, v20
	v_bitop3_b32 v20, v21, v20, s75 bitop3:0x36
	v_max_f32_e32 v2, 0, v2
	global_store_dword v[208:209], v20, off offset:256 nt
	v_fma_f32 v18, v120, v2, 0
	v_max_f32_e32 v2, 0, v10
	v_fma_f32 v10, v121, v2, 0
	v_max_f32_e32 v2, 0, v3
	v_fmac_f32_e32 v18, v122, v2
	v_max_f32_e32 v2, 0, v11
	v_fmac_f32_e32 v10, v123, v2
	v_max_f32_e32 v2, 0, v4
	v_fmac_f32_e32 v18, v124, v2
	v_max_f32_e32 v2, 0, v12
	v_fmac_f32_e32 v10, v125, v2
	v_max_f32_e32 v2, 0, v5
	v_fmac_f32_e32 v18, v126, v2
	v_max_f32_e32 v2, 0, v13
	v_fmac_f32_e32 v10, v127, v2
	v_max_f32_e32 v2, 0, v6
	v_fmac_f32_e32 v18, v128, v2
	v_max_f32_e32 v2, 0, v14
	v_fmac_f32_e32 v10, v129, v2
	v_max_f32_e32 v2, 0, v7
	v_fmac_f32_e32 v18, v130, v2
	v_max_f32_e32 v2, 0, v15
	v_fmac_f32_e32 v10, v131, v2
	v_max_f32_e32 v2, 0, v8
	v_fmac_f32_e32 v18, v132, v2
	v_max_f32_e32 v2, 0, v16
	v_fmac_f32_e32 v10, v133, v2
	v_max_f32_e32 v2, 0, v9
	v_fmac_f32_e32 v18, v134, v2
	v_max_f32_e32 v2, 0, v17
	v_add_f32_e32 v3, 0, v18
	v_fmac_f32_e32 v10, v135, v2
	v_ashrrev_i32_e32 v5, 31, v3
	v_add_f32_e32 v4, 0, v10
	v_bitop3_b32 v5, v5, v3, s75 bitop3:0x36
	global_store_dword v[102:103], v5, off offset:384 nt
	v_ashrrev_i32_e32 v5, 31, v4
	v_bitop3_b32 v4, v5, v4, s75 bitop3:0x36
	v_add_u32_e32 v148, 0x80, v148
	global_store_dword v[208:209], v4, off offset:384 nt
	s_cbranch_scc0 .LBB0_797

.LBB0_3056:
	ds_read_b128 v[2:5], v161
	ds_read_b128 v[114:117], v161 offset:32
	ds_read_b128 v[18:21], v161 offset:4608
	ds_read_b128 v[118:121], v161 offset:4640
	ds_read_b128 v[34:37], v161 offset:9216
	ds_read_b128 v[122:125], v161 offset:9248
	ds_read_b128 v[50:53], v161 offset:13824
	ds_read_b128 v[132:135], v161 offset:13856
	s_waitcnt lgkmcnt(7)
	v_mfma_f32_32x32x16_bf16 v[2:17], v[74:77], v[2:5], 0
	s_mov_b32 s10, s9
	s_add_i32 s9, s9, 4
	s_add_i32 s10, s10, 7
	s_cmp_ge_i32 s10, s8
	s_waitcnt lgkmcnt(5)
	v_mfma_f32_32x32x16_bf16 v[18:33], v[74:77], v[18:21], 0
	s_waitcnt lgkmcnt(1)
	v_mfma_f32_32x32x16_bf16 v[50:65], v[74:77], v[50:53], 0
	v_mfma_f32_32x32x16_bf16 v[34:49], v[74:77], v[34:37], 0
	v_mfma_f32_32x32x16_bf16 v[2:17], v[70:73], v[114:117], v[2:17]
	v_mfma_f32_32x32x16_bf16 v[18:33], v[70:73], v[118:121], v[18:33]
	s_waitcnt lgkmcnt(0)
	v_mfma_f32_32x32x16_bf16 v[50:65], v[70:73], v[132:135], v[50:65]
	ds_read_b128 v[114:117], v161 offset:64
	ds_read_b128 v[132:135], v161 offset:96
	v_mfma_f32_32x32x16_bf16 v[34:49], v[70:73], v[122:125], v[34:49]
	s_waitcnt lgkmcnt(1)
	v_mfma_f32_32x32x16_bf16 v[2:17], v[66:69], v[114:117], v[2:17]
	ds_read_b128 v[114:117], v161 offset:4672
	ds_read_b128 v[122:125], v161 offset:4704
	s_waitcnt lgkmcnt(1)
	v_mfma_f32_32x32x16_bf16 v[18:33], v[66:69], v[114:117], v[18:33]
	ds_read_b128 v[114:117], v161 offset:9280
	ds_read_b128 v[118:121], v161 offset:9312
	s_waitcnt lgkmcnt(1)
	v_mfma_f32_32x32x16_bf16 v[34:49], v[66:69], v[114:117], v[34:49]
	ds_read_b128 v[162:165], v161 offset:13888
	ds_read_b128 v[114:117], v161 offset:13920
	v_add_u32_e32 v161, 0x4800, v161
	s_waitcnt lgkmcnt(1)
	v_mfma_f32_32x32x16_bf16 v[50:65], v[66:69], v[162:165], v[50:65]
	v_mfma_f32_32x32x16_bf16 v[2:17], v[78:81], v[132:135], v[2:17]
	v_lshlrev_b64 v[132:133], 2, v[148:149]
	v_mfma_f32_32x32x16_bf16 v[18:33], v[78:81], v[122:125], v[18:33]
	s_nop 7
	s_nop 1
	v_max_f32_e32 v2, 0, v2
	v_max_f32_e32 v10, 0, v10
	v_mfma_f32_32x32x16_bf16 v[34:49], v[78:81], v[118:121], v[34:49]
	v_max_f32_e32 v3, 0, v3
	v_max_f32_e32 v18, 0, v18
	v_max_f32_e32 v26, 0, v26
	s_waitcnt lgkmcnt(0)
	v_mfma_f32_32x32x16_bf16 v[50:65], v[78:81], v[114:117], v[50:65]
	s_nop 2
	s_nop 3
	v_max_f32_e32 v34, 0, v34
	v_max_f32_e32 v42, 0, v42
	v_fma_f32 v2, v138, v2, 0
	s_nop 1
	v_max_f32_e32 v50, 0, v50
	v_max_f32_e32 v58, 0, v58
	v_max_f32_e32 v11, 0, v11
	v_max_f32_e32 v4, 0, v4
	v_max_f32_e32 v19, 0, v19
	v_max_f32_e32 v27, 0, v27
	v_max_f32_e32 v35, 0, v35
	v_max_f32_e32 v43, 0, v43
	v_max_f32_e32 v51, 0, v51
	v_max_f32_e32 v59, 0, v59
	v_fma_f32 v10, v139, v10, 0
	v_fma_f32 v18, v138, v18, 0
	v_fma_f32 v26, v139, v26, 0
	v_fma_f32 v34, v138, v34, 0
	v_fma_f32 v42, v139, v42, 0
	v_fma_f32 v50, v138, v50, 0
	v_fma_f32 v58, v139, v58, 0
	v_fmac_f32_e32 v2, v140, v3
	v_max_f32_e32 v12, 0, v12
	v_max_f32_e32 v5, 0, v5
	v_max_f32_e32 v20, 0, v20
	v_max_f32_e32 v28, 0, v28
	v_max_f32_e32 v36, 0, v36
	v_max_f32_e32 v44, 0, v44
	v_max_f32_e32 v52, 0, v52
	v_max_f32_e32 v60, 0, v60
	v_fmac_f32_e32 v10, v141, v11
	v_fmac_f32_e32 v18, v140, v19
	v_fmac_f32_e32 v26, v141, v27
	v_fmac_f32_e32 v34, v140, v35
	v_fmac_f32_e32 v42, v141, v43
	v_fmac_f32_e32 v50, v140, v51
	v_fmac_f32_e32 v58, v141, v59
	v_fmac_f32_e32 v2, v142, v4
	v_max_f32_e32 v13, 0, v13
	v_max_f32_e32 v6, 0, v6
	v_max_f32_e32 v21, 0, v21
	v_max_f32_e32 v29, 0, v29
	v_max_f32_e32 v37, 0, v37
	v_max_f32_e32 v45, 0, v45
	v_max_f32_e32 v53, 0, v53
	v_max_f32_e32 v61, 0, v61
	v_fmac_f32_e32 v10, v143, v12
	v_fmac_f32_e32 v18, v142, v20
	v_fmac_f32_e32 v26, v143, v28
	v_fmac_f32_e32 v34, v142, v36
	v_fmac_f32_e32 v42, v143, v44
	v_fmac_f32_e32 v50, v142, v52
	v_fmac_f32_e32 v58, v143, v60
	v_fmac_f32_e32 v2, v144, v5
	v_max_f32_e32 v14, 0, v14
	v_max_f32_e32 v7, 0, v7
	v_max_f32_e32 v22, 0, v22
	v_max_f32_e32 v30, 0, v30
	v_max_f32_e32 v38, 0, v38
	v_max_f32_e32 v46, 0, v46
	v_max_f32_e32 v54, 0, v54
	v_max_f32_e32 v62, 0, v62
	v_fmac_f32_e32 v10, v145, v13
	v_fmac_f32_e32 v18, v144, v21
	v_fmac_f32_e32 v26, v145, v29
	v_fmac_f32_e32 v34, v144, v37
	v_fmac_f32_e32 v42, v145, v45
	v_fmac_f32_e32 v50, v144, v53
	v_fmac_f32_e32 v58, v145, v61
	v_fmac_f32_e32 v2, v150, v6
	v_max_f32_e32 v15, 0, v15
	v_max_f32_e32 v8, 0, v8
	v_max_f32_e32 v23, 0, v23
	v_max_f32_e32 v31, 0, v31
	v_max_f32_e32 v39, 0, v39
	v_max_f32_e32 v47, 0, v47
	v_max_f32_e32 v55, 0, v55
	v_max_f32_e32 v63, 0, v63
	v_fmac_f32_e32 v10, v151, v14
	v_fmac_f32_e32 v18, v150, v22
	v_fmac_f32_e32 v26, v151, v30
	v_fmac_f32_e32 v34, v150, v38
	v_fmac_f32_e32 v42, v151, v46
	v_fmac_f32_e32 v50, v150, v54
	v_fmac_f32_e32 v58, v151, v62
	v_fmac_f32_e32 v2, v152, v7
	v_max_f32_e32 v16, 0, v16
	v_max_f32_e32 v9, 0, v9
	v_max_f32_e32 v24, 0, v24
	v_max_f32_e32 v32, 0, v32
	v_max_f32_e32 v40, 0, v40
	v_max_f32_e32 v48, 0, v48
	v_max_f32_e32 v56, 0, v56
	v_max_f32_e32 v64, 0, v64
	v_fmac_f32_e32 v10, v153, v15
	v_fmac_f32_e32 v18, v152, v23
	v_fmac_f32_e32 v26, v153, v31
	v_fmac_f32_e32 v34, v152, v39
	v_fmac_f32_e32 v42, v153, v47
	v_fmac_f32_e32 v50, v152, v55
	v_fmac_f32_e32 v58, v153, v63
	v_fmac_f32_e32 v2, v154, v8
	v_max_f32_e32 v17, 0, v17
	v_max_f32_e32 v25, 0, v25
	v_max_f32_e32 v33, 0, v33
	v_max_f32_e32 v41, 0, v41
	v_max_f32_e32 v49, 0, v49
	v_max_f32_e32 v57, 0, v57
	v_max_f32_e32 v65, 0, v65
	v_fmac_f32_e32 v10, v155, v16
	v_fmac_f32_e32 v18, v154, v24
	v_fmac_f32_e32 v26, v155, v32
	v_fmac_f32_e32 v34, v154, v40
	v_fmac_f32_e32 v42, v155, v48
	v_fmac_f32_e32 v50, v154, v56
	v_fmac_f32_e32 v58, v155, v64
	v_fmac_f32_e32 v2, v156, v9
	v_fmac_f32_e32 v10, v157, v17
	v_fmac_f32_e32 v18, v156, v25
	v_fmac_f32_e32 v26, v157, v33
	v_fmac_f32_e32 v34, v156, v41
	v_fmac_f32_e32 v42, v157, v49
	v_fmac_f32_e32 v50, v156, v57
	v_fmac_f32_e32 v58, v157, v65
	v_add_f32_e32 v2, 0, v2
	v_add_f32_e32 v3, 0, v10
	v_add_f32_e32 v4, 0, v18
	v_add_f32_e32 v5, 0, v26
	v_add_f32_e32 v6, 0, v34
	v_add_f32_e32 v7, 0, v42
	v_add_f32_e32 v8, 0, v50
	v_add_f32_e32 v9, 0, v58
	v_ashrrev_i32_e32 v10, 31, v2
	v_add_u32_e32 v148, 0x80, v148
	v_lshl_add_u64 v[122:123], v[128:129], 0, v[132:133]
	v_ashrrev_i32_e32 v11, 31, v3
	v_ashrrev_i32_e32 v12, 31, v4
	v_ashrrev_i32_e32 v13, 31, v5
	v_ashrrev_i32_e32 v14, 31, v6
	v_ashrrev_i32_e32 v15, 31, v7
	v_ashrrev_i32_e32 v16, 31, v8
	v_ashrrev_i32_e32 v17, 31, v9
	v_bitop3_b32 v2, v10, v2, s57 bitop3:0x36
	v_lshl_add_u64 v[118:119], v[130:131], 0, v[132:133]
	v_bitop3_b32 v3, v11, v3, s57 bitop3:0x36
	v_bitop3_b32 v4, v12, v4, s57 bitop3:0x36
	v_bitop3_b32 v5, v13, v5, s57 bitop3:0x36
	v_bitop3_b32 v6, v14, v6, s57 bitop3:0x36
	v_bitop3_b32 v7, v15, v7, s57 bitop3:0x36
	v_bitop3_b32 v8, v16, v8, s57 bitop3:0x36
	v_bitop3_b32 v9, v17, v9, s57 bitop3:0x36
	global_store_dword v[122:123], v2, off nt
	global_store_dword v[118:119], v3, off nt
	global_store_dword v[122:123], v4, off offset:128 nt
	global_store_dword v[118:119], v5, off offset:128 nt
	global_store_dword v[122:123], v6, off offset:256 nt
	global_store_dword v[118:119], v7, off offset:256 nt
	global_store_dword v[122:123], v8, off offset:384 nt
	global_store_dword v[118:119], v9, off offset:384 nt
	s_cbranch_scc0 .LBB0_3056
